# grp0 attention: all waves via map0 path + S-type software-pipelined far-tile loop (barrier after QK, cross-iteration K/V fragment prefetch, softmax VALU interleaved in PV MFMAs)
# speedup vs baseline: 1.0007x; 1.0007x over previous
.LBB0_529:
	s_or_b64 exec, exec, s[4:5]
	s_ashr_i32 s44, s87, 3
	s_lshl_b32 s4, s87, 7
	s_ashr_i32 s45, s44, 31
	s_sub_i32 s86, s53, s4
	s_lshl_b32 s96, s84, 23
	s_lshl_b64 s[36:37], s[44:45], 22
	s_add_u32 s4, s92, s36
	s_addc_u32 s5, s93, s37
	s_add_u32 s4, s4, s96
	s_addc_u32 s5, s5, 0
	s_add_u32 s48, s4, 0x4000000
	s_addc_u32 s49, s5, 0
	s_lshl_b32 s85, s86, 7
	s_lshl_b32 s6, s84, 2
	v_and_b32_e32 v154, 31, v153
	v_mov_b32_e32 v0, s6
	s_or_b32 s6, s85, s71
	v_or_b32_e32 v132, s6, v154
	v_ashrrev_i32_e32 v133, 31, v132
	v_readlane_b32 s8, v254, 32
	v_lshlrev_b64 v[2:3], 8, v[132:133]
	v_bfe_u32 v155, v153, 5, 1
	v_readlane_b32 s12, v254, 36
	v_readlane_b32 s13, v254, 37
	v_lshl_add_u64 v[2:3], s[4:5], 0, v[2:3]
	v_bfe_u32 v140, v153, 4, 2
	s_nop 2
	global_load_dword v6, v0, s[12:13] offset:480
	global_load_dword v7, v0, s[12:13] offset:992
	v_lshl_add_u64 v[2:3], v[2:3], 0, s[26:27]
	v_lshlrev_b32_e32 v130, 4, v155
	v_mov_b32_e32 v131, v1
	v_or_b32_e32 v0, s62, v140
	v_lshl_add_u64 v[2:3], v[2:3], 0, v[130:131]
	v_lshlrev_b32_e32 v8, 4, v153
	v_lshlrev_b32_e32 v161, 4, v0
	global_load_dwordx4 v[110:113], v[2:3], off
	global_load_dwordx4 v[106:109], v[2:3], off offset:32
	global_load_dwordx4 v[102:105], v[2:3], off offset:64
	global_load_dwordx4 v[98:101], v[2:3], off offset:96
	v_and_b32_e32 v160, 0xf0, v8
	v_lshlrev_b32_e32 v2, 8, v0
	v_and_b32_e32 v0, 0x70, v161
	v_bitop3_b32 v0, v0, v2, v160 bitop3:0xde
	v_bfe_u32 v2, v153, 2, 3
	s_mov_b32 s6, 0xffffff3
	v_bitop3_b32 v141, v2, s6, v148 bitop3:0xc8
	v_lshrrev_b32_e32 v2, 1, v153
	v_readlane_b32 s18, v254, 42
	s_cmp_lg_u32 0, -1
	v_and_b32_e32 v143, 8, v2
	v_or_b32_e32 v3, s73, v155
	v_and_b32_e32 v159, 48, v8
	v_readlane_b32 s9, v254, 33
	s_cselect_b32 s18, 0, 0
	v_or3_b32 v2, v141, v143, s72
	v_lshl_or_b32 v3, v3, 6, v159
	s_add_i32 s7, s74, 0xc000
	v_lshl_or_b32 v2, v2, 8, v3
	s_mov_b32 m0, s7
	v_lshl_add_u64 v[134:135], s[4:5], 0, v[0:1]
	s_mov_b64 s[8:9], 0x4002000
	s_add_i32 s6, s74, 0xe000
	v_mov_b32_e32 v3, v1
	global_load_lds_dwordx4 v0, s[48:49]
	v_lshl_add_u64 v[4:5], v[134:135], 0, s[8:9]
	s_mov_b32 m0, s6
	v_lshl_add_u64 v[136:137], s[4:5], 0, v[2:3]
	s_mov_b64 s[4:5], 0x8000000
	global_load_lds_dwordx4 v[4:5], off
	v_lshl_add_u64 v[2:3], v[136:137], 0, s[4:5]
	s_mov_b32 m0, s74
	s_mov_b64 s[4:5], 0x8002000
	global_load_lds_dwordx4 v[2:3], off
	v_lshl_add_u64 v[2:3], v[136:137], 0, s[4:5]
	s_add_i32 m0, s74, 0x2000
	s_mov_b64 s[4:5], 0x4004000
	global_load_lds_dwordx4 v[2:3], off
	v_lshl_add_u64 v[2:3], v[134:135], 0, s[4:5]
	s_add_i32 m0, s74, 0x10000
	s_mov_b64 s[4:5], 0x4006000
	global_load_lds_dwordx4 v[2:3], off
	v_lshl_add_u64 v[2:3], v[134:135], 0, s[4:5]
	s_add_i32 m0, s74, 0x12000
	s_mov_b64 s[4:5], 0x4008000
	global_load_lds_dwordx4 v[2:3], off
	s_waitcnt vmcnt(0) lgkmcnt(0)
	s_barrier
	v_lshl_add_u64 v[2:3], v[134:135], 0, s[4:5]
	s_add_i32 m0, s74, 0x14000
	s_mov_b64 s[4:5], 0x400a000
	global_load_lds_dwordx4 v[2:3], off
	v_lshl_add_u64 v[2:3], v[134:135], 0, s[4:5]
	s_add_i32 m0, s74, 0x16000
	s_mov_b64 s[4:5], 0x8004000
	global_load_lds_dwordx4 v[2:3], off
	v_lshl_add_u64 v[2:3], v[136:137], 0, s[4:5]
	s_add_i32 m0, s74, 0x4000
	s_mov_b64 s[4:5], 0x8006000
	global_load_lds_dwordx4 v[2:3], off
	v_lshl_add_u64 v[2:3], v[136:137], 0, s[4:5]
	s_add_i32 m0, s74, 0x6000
	v_lshlrev_b32_e32 v4, 6, v153
	global_load_lds_dwordx4 v[2:3], off
	v_lshlrev_b32_e32 v2, 3, v153
	v_and_b32_e32 v3, 0xc0, v8
	v_and_or_b32 v2, v2, 24, v3
	v_lshlrev_b32_e32 v3, 1, v153
	v_and_b32_e32 v3, 32, v3
	v_and_b32_e32 v4, 0x800, v4
	v_or3_b32 v2, v2, v3, v4
	v_lshlrev_b32_e32 v156, 8, v154
	v_lshlrev_b32_e32 v164, 4, v154
	v_and_b32_e32 v131, 63, v153
	s_waitcnt vmcnt(0)
	v_mul_f32_e32 v142, 0x3fb8aa3b, v6
	v_mul_f32_e32 v133, 0x3fb8aa3b, v7
	v_add_u32_e32 v157, s18, v2
	s_mov_b64 s[4:5], -1
	s_and_b64 vcc, exec, s[28:29]
	v_and_b32_e32 v162, 0x70, v164
	v_add_u32_e32 v163, 0, v156
	v_lshlrev_b32_e32 v158, 2, v155
	v_readlane_b32 s10, v254, 34
	v_readlane_b32 s11, v254, 35
	v_readlane_b32 s14, v254, 38
	v_readlane_b32 s15, v254, 39
	v_readlane_b32 s16, v254, 40
	v_readlane_b32 s17, v254, 41
	v_readlane_b32 s19, v254, 43
	v_readlane_b32 s20, v254, 44
	v_readlane_b32 s21, v254, 45
	v_readlane_b32 s22, v254, 46
	v_readlane_b32 s23, v254, 47
	s_branch .LBB0_562
	v_bitop3_b32 v167, v130, v162, s64 bitop3:0x36
	v_add_u32_e32 v6, v163, v167
	ds_read_b128 v[2:5], v6 offset:49152
	ds_read_b128 v[6:9], v6 offset:57344
	s_movk_i32 s4, 0xa0
	v_bitop3_b32 v168, v130, v162, s4 bitop3:0x36
	v_add_u32_e32 v38, v163, v168
	s_waitcnt lgkmcnt(0)
	v_mfma_f32_32x32x16_bf16 v[18:33], v[2:5], v[110:113], 0
	ds_read_b128 v[34:37], v38 offset:49152
	ds_read_b128 v[38:41], v38 offset:57344
	s_movk_i32 s4, 0xc0
	v_bitop3_b32 v169, v130, v162, s4 bitop3:0x36
	v_add_u32_e32 v42, v163, v169
	s_movk_i32 s4, 0xe0
	v_bitop3_b32 v170, v130, v162, s4 bitop3:0x36
	v_add_u32_e32 v46, v163, v170
	v_mfma_f32_32x32x16_bf16 v[2:17], v[6:9], v[110:113], 0
	s_mov_b64 s[4:5], 0x400c000
	s_mov_b32 m0, s7
	v_sub_u32_e32 v166, v158, v132
	s_waitcnt lgkmcnt(1)
	v_mfma_f32_32x32x16_bf16 v[18:33], v[34:37], v[106:109], v[18:33]
	ds_read_b128 v[34:37], v42 offset:49152
	ds_read_b128 v[42:45], v42 offset:57344
	s_waitcnt lgkmcnt(2)
	v_mfma_f32_32x32x16_bf16 v[2:17], v[38:41], v[106:109], v[2:17]
	ds_read_b128 v[38:41], v46 offset:49152
	ds_read_b128 v[46:49], v46 offset:57344
	s_waitcnt vmcnt(4) lgkmcnt(0)
	s_barrier
	s_waitcnt lgkmcnt(3)
	v_mfma_f32_32x32x16_bf16 v[18:33], v[34:37], v[102:105], v[18:33]
	v_lshl_add_u64 v[34:35], v[134:135], 0, s[4:5]
	s_mov_b64 s[4:5], 0x400e000
	global_load_lds_dwordx4 v[34:35], off
	v_lshl_add_u64 v[34:35], v[134:135], 0, s[4:5]
	s_mov_b32 m0, s6
	s_mov_b64 s[4:5], 0x8008000
	global_load_lds_dwordx4 v[34:35], off
	v_lshl_add_u64 v[34:35], v[136:137], 0, s[4:5]
	s_mov_b32 m0, s81
	s_mov_b64 s[4:5], 0x800a000
	global_load_lds_dwordx4 v[34:35], off
	v_lshl_add_u64 v[34:35], v[136:137], 0, s[4:5]
	s_mov_b32 m0, s82
	s_waitcnt lgkmcnt(0)
	v_mfma_f32_32x32x16_bf16 v[2:17], v[42:45], v[102:105], v[2:17]
	global_load_lds_dwordx4 v[34:35], off
	s_add_i32 s4, s85, 0xd9
	s_cmpk_gt_u32 s4, 0x172
	v_mfma_f32_32x32x16_bf16 v[18:33], v[38:41], v[98:101], v[18:33]
	v_mfma_f32_32x32x16_bf16 v[2:17], v[46:49], v[98:101], v[2:17]
	s_cbranch_scc1 .LBB0_532
	v_mov_b32_e32 v58, v166
	s_add_i32 s4, 0, 0x18800
	v_add_u32_e32 v36, 1, v58
	v_med3_i32 v37, v36, s65, v146
	v_med3_i32 v36, v36, s69, v147
	v_lshl_add_u32 v38, v36, 2, s4
	v_add_u32_e32 v36, 2, v58
	v_med3_i32 v39, v36, s65, v146
	v_med3_i32 v36, v36, s69, v147
	v_lshl_add_u32 v40, v36, 2, s4
	v_add_u32_e32 v36, 3, v58
	v_med3_i32 v34, v58, s65, v146
	v_med3_i32 v35, v58, s69, v147
	v_med3_i32 v41, v36, s65, v146
	v_med3_i32 v36, v36, s69, v147
	v_lshl_add_u32 v34, v34, 2, s4
	v_lshl_add_u32 v35, v35, 2, s4
	v_lshl_add_u32 v37, v37, 2, s4
	v_lshl_add_u32 v39, v39, 2, s4
	v_lshl_add_u32 v41, v41, 2, s4
	v_lshl_add_u32 v42, v36, 2, s4
	ds_read_b32 v34, v34 offset:512
	ds_read_b32 v36, v35 offset:640
	ds_read_b32 v35, v37 offset:512
	ds_read_b32 v37, v38 offset:640
	ds_read_b32 v38, v39 offset:512
	ds_read_b32 v40, v40 offset:640
	ds_read_b32 v39, v41 offset:512
	ds_read_b32 v41, v42 offset:640
	v_add_u32_e32 v42, 8, v58
	v_med3_i32 v43, v42, s65, v146
	v_med3_i32 v42, v42, s69, v147
	v_lshl_add_u32 v44, v42, 2, s4
	v_add_u32_e32 v42, 9, v58
	v_med3_i32 v45, v42, s65, v146
	v_med3_i32 v42, v42, s69, v147
	v_lshl_add_u32 v46, v42, 2, s4
	v_add_u32_e32 v42, 10, v58
	v_med3_i32 v47, v42, s65, v146
	v_med3_i32 v42, v42, s69, v147
	v_lshl_add_u32 v48, v42, 2, s4
	v_add_u32_e32 v42, 11, v58
	v_med3_i32 v49, v42, s65, v146
	v_med3_i32 v42, v42, s69, v147
	v_lshl_add_u32 v43, v43, 2, s4
	v_lshl_add_u32 v45, v45, 2, s4
	v_lshl_add_u32 v47, v47, 2, s4
	v_lshl_add_u32 v49, v49, 2, s4
	v_lshl_add_u32 v50, v42, 2, s4
	ds_read_b32 v42, v43 offset:512
	ds_read_b32 v44, v44 offset:640
	ds_read_b32 v43, v45 offset:512
	ds_read_b32 v45, v46 offset:640
	ds_read_b32 v46, v47 offset:512
	ds_read_b32 v48, v48 offset:640
	ds_read_b32 v47, v49 offset:512
	ds_read_b32 v49, v50 offset:640
	v_add_u32_e32 v50, 16, v58
	v_med3_i32 v51, v50, s65, v146
	v_med3_i32 v50, v50, s69, v147
	v_lshl_add_u32 v52, v50, 2, s4
	v_add_u32_e32 v50, 17, v58
	v_med3_i32 v53, v50, s65, v146
	v_med3_i32 v50, v50, s69, v147
	v_lshl_add_u32 v54, v50, 2, s4
	v_add_u32_e32 v50, 18, v58
	v_med3_i32 v55, v50, s65, v146
	v_med3_i32 v50, v50, s69, v147
	v_lshl_add_u32 v56, v50, 2, s4
	v_add_u32_e32 v50, 19, v58
	v_add_u32_e32 v61, 25, v58
	v_med3_i32 v57, v50, s65, v146
	v_med3_i32 v50, v50, s69, v147
	v_med3_i32 v62, v61, s65, v146
	v_lshl_add_u32 v51, v51, 2, s4
	v_lshl_add_u32 v53, v53, 2, s4
	v_lshl_add_u32 v55, v55, 2, s4
	v_lshl_add_u32 v57, v57, 2, s4
	v_lshl_add_u32 v59, v50, 2, s4
	v_lshl_add_u32 v64, v62, 2, s4
	v_add_u32_e32 v62, 26, v58
	ds_read_b32 v50, v51 offset:512
	ds_read_b32 v52, v52 offset:640
	ds_read_b32 v51, v53 offset:512
	ds_read_b32 v53, v54 offset:640
	ds_read_b32 v54, v55 offset:512
	ds_read_b32 v56, v56 offset:640
	ds_read_b32 v55, v57 offset:512
	ds_read_b32 v57, v59 offset:640
	v_add_u32_e32 v59, 24, v58
	v_med3_i32 v63, v62, s65, v146
	v_med3_i32 v62, v62, s69, v147
	v_add_u32_e32 v58, 27, v58
	v_med3_i32 v60, v59, s65, v146
	v_med3_i32 v59, v59, s69, v147
	v_med3_i32 v61, v61, s69, v147
	v_lshl_add_u32 v66, v62, 2, s4
	v_med3_i32 v62, v58, s65, v146
	v_lshl_add_u32 v60, v60, 2, s4
	v_lshl_add_u32 v59, v59, 2, s4
	v_lshl_add_u32 v61, v61, 2, s4
	v_lshl_add_u32 v63, v63, 2, s4
	v_med3_i32 v58, v58, s69, v147
	v_lshl_add_u32 v65, v62, 2, s4
	v_lshl_add_u32 v67, v58, 2, s4
	ds_read_b32 v58, v60 offset:512
	ds_read_b32 v60, v59 offset:640
	ds_read_b32 v62, v63 offset:512
	ds_read_b32 v63, v65 offset:512
	ds_read_b32 v59, v64 offset:512
	ds_read_b32 v65, v67 offset:640
	ds_read_b32 v64, v66 offset:640
	ds_read_b32 v61, v61 offset:640
	s_waitcnt lgkmcnt(0)
	v_pk_add_f32 v[32:33], v[32:33], v[62:63]
	v_pk_add_f32 v[30:31], v[30:31], v[58:59]
	v_pk_add_f32 v[28:29], v[28:29], v[54:55]
	v_pk_add_f32 v[26:27], v[26:27], v[50:51]
	v_pk_add_f32 v[24:25], v[24:25], v[46:47]
	v_pk_add_f32 v[22:23], v[22:23], v[42:43]
	v_pk_add_f32 v[20:21], v[20:21], v[38:39]
	v_pk_add_f32 v[18:19], v[18:19], v[34:35]
	v_pk_add_f32 v[16:17], v[16:17], v[64:65]
	v_pk_add_f32 v[14:15], v[14:15], v[60:61]
	v_pk_add_f32 v[12:13], v[12:13], v[56:57]
	v_pk_add_f32 v[10:11], v[10:11], v[52:53]
	v_pk_add_f32 v[8:9], v[8:9], v[48:49]
	v_pk_add_f32 v[6:7], v[6:7], v[44:45]
	v_pk_add_f32 v[4:5], v[4:5], v[40:41]
	v_pk_add_f32 v[2:3], v[2:3], v[36:37]

.LBB0_562:
	s_and_b64 vcc, exec, s[4:5]
	s_cbranch_vccz .LBB0_594
	v_bitop3_b32 v164, v130, v164, s68 bitop3:0x78
	v_add_u32_e32 v164, s26, v164
	v_add_u32_e32 v0, v163, v164
	s_nop 7
	ds_read_b128 v[2:5], v0 offset:49152
	v_bitop3_b32 v165, v130, v162, 32 bitop3:0x36
	v_add_u32_e32 v165, s26, v165
	v_bitop3_b32 v166, v130, v162, 64 bitop3:0x36
	v_add_u32_e32 v166, s26, v166
	s_movk_i32 s4, 0x60
	v_bitop3_b32 v167, v130, v162, s4 bitop3:0x36
	v_add_u32_e32 v167, s26, v167
	s_add_i32 s4, s85, 0xd9
	s_cmpk_gt_u32 s4, 0x172
	s_waitcnt lgkmcnt(0)
	v_mfma_f32_32x32x16_bf16 v[18:33], v[2:5], v[110:113], 0
	ds_read_b128 v[2:5], v0 offset:57344
	v_add_u32_e32 v0, v163, v165
	ds_read_b128 v[34:37], v0 offset:49152
	s_waitcnt lgkmcnt(0)
	v_mfma_f32_32x32x16_bf16 v[2:17], v[2:5], v[110:113], 0
	v_mfma_f32_32x32x16_bf16 v[18:33], v[34:37], v[106:109], v[18:33]
	ds_read_b128 v[34:37], v0 offset:57344
	v_add_u32_e32 v0, v163, v166
	s_waitcnt lgkmcnt(0)
	v_mfma_f32_32x32x16_bf16 v[2:17], v[34:37], v[106:109], v[2:17]
	ds_read_b128 v[34:37], v0 offset:49152
	s_waitcnt lgkmcnt(0)
	v_mfma_f32_32x32x16_bf16 v[18:33], v[34:37], v[102:105], v[18:33]
	ds_read_b128 v[34:37], v0 offset:57344
	v_add_u32_e32 v0, v163, v167
	s_waitcnt lgkmcnt(0)
	v_mfma_f32_32x32x16_bf16 v[2:17], v[34:37], v[102:105], v[2:17]
	ds_read_b128 v[34:37], v0 offset:49152
	s_waitcnt lgkmcnt(0)
	v_mfma_f32_32x32x16_bf16 v[18:33], v[34:37], v[98:101], v[18:33]
	ds_read_b128 v[34:37], v0 offset:57344
	s_waitcnt lgkmcnt(0)
	v_mfma_f32_32x32x16_bf16 v[2:17], v[34:37], v[98:101], v[2:17]
	s_cbranch_scc1 .LBB0_565
	v_sub_u32_e32 v0, v158, v132
	s_add_i32 s4, 0, 0x18800
	v_add_u32_e32 v36, 1, v0
	v_med3_i32 v37, v36, s65, v146
	v_med3_i32 v36, v36, s69, v147
	v_lshl_add_u32 v38, v36, 2, s4
	v_add_u32_e32 v36, 2, v0
	v_med3_i32 v39, v36, s65, v146
	v_med3_i32 v36, v36, s69, v147
	v_lshl_add_u32 v40, v36, 2, s4
	v_add_u32_e32 v36, 3, v0
	v_med3_i32 v34, v0, s65, v146
	v_med3_i32 v35, v0, s69, v147
	v_med3_i32 v41, v36, s65, v146
	v_med3_i32 v36, v36, s69, v147
	v_lshl_add_u32 v34, v34, 2, s4
	v_lshl_add_u32 v35, v35, 2, s4
	v_lshl_add_u32 v37, v37, 2, s4
	v_lshl_add_u32 v39, v39, 2, s4
	v_lshl_add_u32 v41, v41, 2, s4
	v_lshl_add_u32 v42, v36, 2, s4
	ds_read_b32 v34, v34 offset:512
	ds_read_b32 v36, v35 offset:640
	ds_read_b32 v35, v37 offset:512
	ds_read_b32 v37, v38 offset:640
	ds_read_b32 v38, v39 offset:512
	ds_read_b32 v40, v40 offset:640
	ds_read_b32 v39, v41 offset:512
	ds_read_b32 v41, v42 offset:640
	v_add_u32_e32 v42, 8, v0
	v_med3_i32 v43, v42, s65, v146
	v_med3_i32 v42, v42, s69, v147
	v_lshl_add_u32 v44, v42, 2, s4
	v_add_u32_e32 v42, 9, v0
	v_med3_i32 v45, v42, s65, v146
	v_med3_i32 v42, v42, s69, v147
	v_lshl_add_u32 v46, v42, 2, s4
	v_add_u32_e32 v42, 10, v0
	v_med3_i32 v47, v42, s65, v146
	v_med3_i32 v42, v42, s69, v147
	v_lshl_add_u32 v48, v42, 2, s4
	v_add_u32_e32 v42, 11, v0
	v_med3_i32 v49, v42, s65, v146
	v_med3_i32 v42, v42, s69, v147
	v_lshl_add_u32 v43, v43, 2, s4
	v_lshl_add_u32 v45, v45, 2, s4
	v_lshl_add_u32 v47, v47, 2, s4
	v_lshl_add_u32 v49, v49, 2, s4
	v_lshl_add_u32 v50, v42, 2, s4
	ds_read_b32 v42, v43 offset:512
	ds_read_b32 v44, v44 offset:640
	ds_read_b32 v43, v45 offset:512
	ds_read_b32 v45, v46 offset:640
	ds_read_b32 v46, v47 offset:512
	ds_read_b32 v48, v48 offset:640
	ds_read_b32 v47, v49 offset:512
	ds_read_b32 v49, v50 offset:640
	v_add_u32_e32 v50, 16, v0
	v_med3_i32 v51, v50, s65, v146
	v_med3_i32 v50, v50, s69, v147
	v_lshl_add_u32 v52, v50, 2, s4
	v_add_u32_e32 v50, 17, v0
	v_med3_i32 v53, v50, s65, v146
	v_med3_i32 v50, v50, s69, v147
	v_lshl_add_u32 v54, v50, 2, s4
	v_add_u32_e32 v50, 18, v0
	v_med3_i32 v55, v50, s65, v146
	v_med3_i32 v50, v50, s69, v147
	v_lshl_add_u32 v56, v50, 2, s4
	v_add_u32_e32 v50, 19, v0
	v_med3_i32 v57, v50, s65, v146
	v_med3_i32 v50, v50, s69, v147
	v_lshl_add_u32 v51, v51, 2, s4
	v_lshl_add_u32 v53, v53, 2, s4
	v_lshl_add_u32 v55, v55, 2, s4
	v_lshl_add_u32 v57, v57, 2, s4
	v_lshl_add_u32 v58, v50, 2, s4
	ds_read_b32 v50, v51 offset:512
	ds_read_b32 v52, v52 offset:640
	ds_read_b32 v51, v53 offset:512
	ds_read_b32 v53, v54 offset:640
	ds_read_b32 v54, v55 offset:512
	ds_read_b32 v56, v56 offset:640
	ds_read_b32 v55, v57 offset:512
	ds_read_b32 v57, v58 offset:640
	v_add_u32_e32 v58, 24, v0
	v_med3_i32 v59, v58, s65, v146
	v_med3_i32 v58, v58, s69, v147
	v_lshl_add_u32 v60, v58, 2, s4
	v_add_u32_e32 v58, 25, v0
	v_med3_i32 v61, v58, s65, v146
	v_med3_i32 v58, v58, s69, v147
	v_lshl_add_u32 v66, v58, 2, s4
	v_add_u32_e32 v58, 26, v0
	v_med3_i32 v62, v58, s65, v146
	v_med3_i32 v58, v58, s69, v147
	v_add_u32_e32 v0, 27, v0
	v_lshl_add_u32 v64, v58, 2, s4
	v_med3_i32 v58, v0, s65, v146
	v_lshl_add_u32 v59, v59, 2, s4
	v_lshl_add_u32 v61, v61, 2, s4
	v_lshl_add_u32 v62, v62, 2, s4
	v_med3_i32 v0, v0, s69, v147
	v_lshl_add_u32 v63, v58, 2, s4
	v_lshl_add_u32 v0, v0, 2, s4
	ds_read_b32 v58, v59 offset:512
	ds_read_b32 v60, v60 offset:640
	ds_read_b32 v62, v62 offset:512
	ds_read_b32 v63, v63 offset:512
	ds_read_b32 v59, v61 offset:512
	ds_read_b32 v65, v0 offset:640
	ds_read_b32 v64, v64 offset:640
	ds_read_b32 v61, v66 offset:640
	s_waitcnt lgkmcnt(0)
	v_pk_add_f32 v[32:33], v[32:33], v[62:63]
	v_pk_add_f32 v[30:31], v[30:31], v[58:59]
	v_pk_add_f32 v[28:29], v[28:29], v[54:55]
	v_pk_add_f32 v[26:27], v[26:27], v[50:51]
	v_pk_add_f32 v[24:25], v[24:25], v[46:47]
	v_pk_add_f32 v[22:23], v[22:23], v[42:43]
	v_pk_add_f32 v[20:21], v[20:21], v[38:39]
	v_pk_add_f32 v[18:19], v[18:19], v[34:35]
	v_pk_add_f32 v[16:17], v[16:17], v[64:65]
	v_pk_add_f32 v[14:15], v[14:15], v[60:61]
	v_pk_add_f32 v[12:13], v[12:13], v[56:57]
	v_pk_add_f32 v[10:11], v[10:11], v[52:53]
	v_pk_add_f32 v[8:9], v[8:9], v[48:49]
	v_pk_add_f32 v[6:7], v[6:7], v[44:45]
	v_pk_add_f32 v[4:5], v[4:5], v[40:41]
	v_pk_add_f32 v[2:3], v[2:3], v[36:37]

.LBB0_570:
	s_add_i32 s10, s97, s96
	s_abs_i32 s11, s10
	s_cmpk_lt_i32 s11, 0xda
	s_cbranch_scc1 .Lfa0_nofast
	s_add_i32 s11, s96, 64
	s_cmpk_eq_i32 s11, 0x3f40
	s_cbranch_scc0 .Lfa0_entry

.Lfa0_entry:
	s_lshl_b32 s10, s95, 14
	s_add_i32 s10, s10, 0xc000
	v_add_u32_e32 v208, s10, v156
	v_add_u32_e32 v252, v208, v164
	ds_read_b128 v[220:223], v252
	v_add_u32_e32 v252, v208, v165
	ds_read_b128 v[224:227], v252
	v_add_u32_e32 v252, v208, v166
	ds_read_b128 v[228:231], v252
	v_add_u32_e32 v252, v208, v167
	ds_read_b128 v[232:235], v252
	v_add_u32_e32 v252, v208, v164
	ds_read_b128 v[236:239], v252 offset:8192
	v_add_u32_e32 v252, v208, v165
	ds_read_b128 v[240:243], v252 offset:8192
	v_add_u32_e32 v252, v208, v166
	ds_read_b128 v[244:247], v252 offset:8192
	v_add_u32_e32 v252, v208, v167
	ds_read_b128 v[248:251], v252 offset:8192
	s_lshl_b32 s10, s6, 14
	v_add_u32_e32 v209, s10, v157
	ds_read_b64_tr_b16 v[168:169], v209 offset:0
	ds_read_b64_tr_b16 v[170:171], v209 offset:256
	ds_read_b64_tr_b16 v[172:173], v209 offset:512
	ds_read_b64_tr_b16 v[174:175], v209 offset:768
	ds_read_b64_tr_b16 v[176:177], v209 offset:1024
	ds_read_b64_tr_b16 v[178:179], v209 offset:1280
	ds_read_b64_tr_b16 v[180:181], v209 offset:1536
	ds_read_b64_tr_b16 v[182:183], v209 offset:1792
	ds_read_b64_tr_b16 v[184:185], v209 offset:4096
	ds_read_b64_tr_b16 v[186:187], v209 offset:4352
	ds_read_b64_tr_b16 v[188:189], v209 offset:4608
	ds_read_b64_tr_b16 v[190:191], v209 offset:4864
	ds_read_b64_tr_b16 v[192:193], v209 offset:5120
	ds_read_b64_tr_b16 v[194:195], v209 offset:5376
	ds_read_b64_tr_b16 v[200:201], v209 offset:5632
	ds_read_b64_tr_b16 v[202:203], v209 offset:5888
	s_waitcnt lgkmcnt(0)
.Lfa0_loop:
	s_mov_b32 s33, s6
	s_lshl_b32 s8, s33, 14
	v_add_u32_e32 v209, s8, v157
	s_lshl_b32 s10, s95, 14
	v_add_u32_e32 v210, s10, v157
	s_lshl_b32 s50, s89, 14
	s_add_i32 s10, s50, 0xc000
	v_add_u32_e32 v208, s10, v156
	s_waitcnt lgkmcnt(15)
	v_mfma_f32_32x32x16_bf16 v[82:97], v[220:223], v[110:113], 0
	v_lshl_add_u64 v[204:205], s[48:49], 0, v[140:141]
	s_mov_b64 s[6:7], 0xaf8c000
	s_add_i32 s18, s74, s8
	v_lshl_add_u64 v[206:207], v[204:205], 0, s[6:7]
	s_add_i32 m0, s18, 0xc000
	s_mov_b64 s[6:7], 0xaf8e000
	global_load_lds_dwordx4 v[206:207], off
	s_waitcnt lgkmcnt(15)
	v_mfma_f32_32x32x16_bf16 v[82:97], v[224:227], v[106:109], v[82:97]
	s_waitcnt lgkmcnt(15)
	v_mfma_f32_32x32x16_bf16 v[82:97], v[228:231], v[102:105], v[82:97]
	v_lshl_add_u64 v[204:205], v[204:205], 0, s[6:7]
	s_add_i32 m0, s18, 0xe000
	s_nop 0
	global_load_lds_dwordx4 v[204:205], off
	s_waitcnt lgkmcnt(15)
	v_mfma_f32_32x32x16_bf16 v[82:97], v[232:235], v[98:101], v[82:97]
	s_waitcnt lgkmcnt(15)
	v_mfma_f32_32x32x16_bf16 v[66:81], v[236:239], v[110:113], 0
	s_waitcnt lgkmcnt(10)
	v_mfma_f32_32x32x16_bf16 v[66:81], v[240:243], v[106:109], v[66:81]
	s_waitcnt lgkmcnt(5)
	v_mfma_f32_32x32x16_bf16 v[66:81], v[244:247], v[102:105], v[66:81]
	s_waitcnt lgkmcnt(0)
	v_mfma_f32_32x32x16_bf16 v[66:81], v[248:251], v[98:101], v[66:81]
	s_waitcnt vmcnt(2)
	s_barrier
	s_andn2_b64 vcc, exec, s[46:47]
	s_cbranch_vccz .Lfa0_shift
.Lfa0_shift_done:
	s_waitcnt lgkmcnt(15)
	v_mfma_f32_32x32x16_bf16 v[18:33], v[126:129], v[168:171], v[18:33]
	v_lshl_add_u64 v[204:205], s[48:49], 0, v[0:1]
	s_mov_b64 s[6:7], 0xef88000
	s_add_i32 s87, s74, s50
	v_lshl_add_u64 v[206:207], v[204:205], 0, s[6:7]
	s_mov_b32 m0, s87
	s_mov_b64 s[6:7], 0xef8a000
	global_load_lds_dwordx4 v[206:207], off
	ds_read_b64_tr_b16 v[168:169], v209 offset:8192
	ds_read_b64_tr_b16 v[170:171], v209 offset:8448
	v_exp_f32_e32 v82, v82
	v_exp_f32_e32 v83, v83
	s_waitcnt lgkmcnt(15)
	v_mfma_f32_32x32x16_bf16 v[50:65], v[126:129], v[172:175], v[50:65]
	ds_read_b64_tr_b16 v[172:173], v209 offset:8704
	ds_read_b64_tr_b16 v[174:175], v209 offset:8960
	v_add_u32_e32 v252, v208, v164
	ds_read_b128 v[220:223], v252
	v_exp_f32_e32 v84, v84
	v_exp_f32_e32 v85, v85
	v_add_f32_e32 v138, 0, v82
	v_add_f32_e32 v138, v83, v138
	s_waitcnt lgkmcnt(15)
	v_mfma_f32_32x32x16_bf16 v[34:49], v[126:129], v[176:179], v[34:49]
	v_lshl_add_u64 v[204:205], v[204:205], 0, s[6:7]
	s_add_i32 m0, s87, 0x2000
	s_nop 0
	global_load_lds_dwordx4 v[204:205], off
	ds_read_b64_tr_b16 v[176:177], v209 offset:9216
	ds_read_b64_tr_b16 v[178:179], v209 offset:9472
	v_exp_f32_e32 v86, v86
	v_exp_f32_e32 v87, v87
	v_add_f32_e32 v138, v84, v138
	v_add_f32_e32 v138, v85, v138
	s_waitcnt lgkmcnt(15)
	v_mfma_f32_32x32x16_bf16 v[2:17], v[126:129], v[180:183], v[2:17]
	ds_read_b64_tr_b16 v[180:181], v209 offset:9728
	ds_read_b64_tr_b16 v[182:183], v209 offset:9984
	v_add_u32_e32 v252, v208, v165
	ds_read_b128 v[224:227], v252
	v_exp_f32_e32 v88, v88
	v_exp_f32_e32 v89, v89
	v_add_f32_e32 v138, v86, v138
	v_add_f32_e32 v138, v87, v138
	s_waitcnt lgkmcnt(15)
	v_mfma_f32_32x32x16_bf16 v[18:33], v[122:125], v[184:187], v[18:33]
	ds_read_b64_tr_b16 v[184:185], v209 offset:12288
	ds_read_b64_tr_b16 v[186:187], v209 offset:12544
	v_exp_f32_e32 v90, v90
	v_exp_f32_e32 v91, v91
	v_add_f32_e32 v138, v88, v138
	v_add_f32_e32 v138, v89, v138
	v_cvt_pk_bf16_f32 v126, v82, v83
	s_waitcnt lgkmcnt(15)
	v_mfma_f32_32x32x16_bf16 v[50:65], v[122:125], v[188:191], v[50:65]
	ds_read_b64_tr_b16 v[188:189], v209 offset:12800
	ds_read_b64_tr_b16 v[190:191], v209 offset:13056
	v_add_u32_e32 v252, v208, v166
	ds_read_b128 v[228:231], v252
	v_exp_f32_e32 v92, v92
	v_exp_f32_e32 v93, v93
	v_add_f32_e32 v138, v90, v138
	v_add_f32_e32 v138, v91, v138
	v_cvt_pk_bf16_f32 v127, v84, v85
	s_waitcnt lgkmcnt(15)
	v_mfma_f32_32x32x16_bf16 v[34:49], v[122:125], v[192:195], v[34:49]
	ds_read_b64_tr_b16 v[192:193], v209 offset:13312
	ds_read_b64_tr_b16 v[194:195], v209 offset:13568
	v_exp_f32_e32 v94, v94
	v_exp_f32_e32 v95, v95
	v_add_f32_e32 v138, v92, v138
	v_add_f32_e32 v138, v93, v138
	v_cvt_pk_bf16_f32 v128, v86, v87
	s_waitcnt lgkmcnt(15)
	v_mfma_f32_32x32x16_bf16 v[2:17], v[122:125], v[200:203], v[2:17]
	ds_read_b64_tr_b16 v[200:201], v209 offset:13824
	ds_read_b64_tr_b16 v[202:203], v209 offset:14080
	v_add_u32_e32 v252, v208, v167
	ds_read_b128 v[232:235], v252
	v_exp_f32_e32 v96, v96
	v_exp_f32_e32 v97, v97
	v_add_f32_e32 v138, v94, v138
	v_add_f32_e32 v138, v95, v138
	v_cvt_pk_bf16_f32 v129, v88, v89
	s_waitcnt lgkmcnt(15)
	v_mfma_f32_32x32x16_bf16 v[18:33], v[118:121], v[168:171], v[18:33]
	ds_read_b64_tr_b16 v[168:169], v210 offset:0
	ds_read_b64_tr_b16 v[170:171], v210 offset:256
	v_exp_f32_e32 v66, v66
	v_exp_f32_e32 v67, v67
	v_add_f32_e32 v138, v96, v138
	v_add_f32_e32 v138, v97, v138
	v_cvt_pk_bf16_f32 v122, v90, v91
	s_waitcnt lgkmcnt(15)
	v_mfma_f32_32x32x16_bf16 v[50:65], v[118:121], v[172:175], v[50:65]
	ds_read_b64_tr_b16 v[172:173], v210 offset:512
	ds_read_b64_tr_b16 v[174:175], v210 offset:768
	v_add_u32_e32 v252, v208, v164
	ds_read_b128 v[236:239], v252 offset:8192
	v_exp_f32_e32 v68, v68
	v_exp_f32_e32 v69, v69
	v_add_f32_e32 v138, v66, v138
	v_add_f32_e32 v138, v67, v138
	v_cvt_pk_bf16_f32 v123, v92, v93
	s_waitcnt lgkmcnt(15)
	v_mfma_f32_32x32x16_bf16 v[34:49], v[118:121], v[176:179], v[34:49]
	ds_read_b64_tr_b16 v[176:177], v210 offset:1024
	ds_read_b64_tr_b16 v[178:179], v210 offset:1280
	v_exp_f32_e32 v70, v70
	v_exp_f32_e32 v71, v71
	v_add_f32_e32 v138, v68, v138
	v_add_f32_e32 v138, v69, v138
	v_cvt_pk_bf16_f32 v124, v94, v95
	s_waitcnt lgkmcnt(15)
	v_mfma_f32_32x32x16_bf16 v[2:17], v[118:121], v[180:183], v[2:17]
	ds_read_b64_tr_b16 v[180:181], v210 offset:1536
	ds_read_b64_tr_b16 v[182:183], v210 offset:1792
	v_add_u32_e32 v252, v208, v165
	ds_read_b128 v[240:243], v252 offset:8192
	v_exp_f32_e32 v72, v72
	v_exp_f32_e32 v73, v73
	v_add_f32_e32 v138, v70, v138
	v_add_f32_e32 v138, v71, v138
	v_cvt_pk_bf16_f32 v125, v96, v97
	s_waitcnt lgkmcnt(15)
	v_mfma_f32_32x32x16_bf16 v[18:33], v[114:117], v[184:187], v[18:33]
	ds_read_b64_tr_b16 v[184:185], v210 offset:4096
	ds_read_b64_tr_b16 v[186:187], v210 offset:4352
	v_exp_f32_e32 v74, v74
	v_exp_f32_e32 v75, v75
	v_add_f32_e32 v138, v72, v138
	v_add_f32_e32 v138, v73, v138
	v_cvt_pk_bf16_f32 v118, v66, v67
	s_waitcnt lgkmcnt(15)
	v_mfma_f32_32x32x16_bf16 v[50:65], v[114:117], v[188:191], v[50:65]
	ds_read_b64_tr_b16 v[188:189], v210 offset:4608
	ds_read_b64_tr_b16 v[190:191], v210 offset:4864
	v_add_u32_e32 v252, v208, v166
	ds_read_b128 v[244:247], v252 offset:8192
	v_exp_f32_e32 v76, v76
	v_exp_f32_e32 v77, v77
	v_add_f32_e32 v138, v74, v138
	v_add_f32_e32 v138, v75, v138
	v_cvt_pk_bf16_f32 v119, v68, v69
	s_waitcnt lgkmcnt(15)
	v_mfma_f32_32x32x16_bf16 v[34:49], v[114:117], v[192:195], v[34:49]
	ds_read_b64_tr_b16 v[192:193], v210 offset:5120
	ds_read_b64_tr_b16 v[194:195], v210 offset:5376
	v_exp_f32_e32 v78, v78
	v_exp_f32_e32 v79, v79
	v_add_f32_e32 v138, v76, v138
	v_add_f32_e32 v138, v77, v138
	v_cvt_pk_bf16_f32 v120, v70, v71
	s_waitcnt lgkmcnt(15)
	v_mfma_f32_32x32x16_bf16 v[2:17], v[114:117], v[200:203], v[2:17]
	ds_read_b64_tr_b16 v[200:201], v210 offset:5632
	ds_read_b64_tr_b16 v[202:203], v210 offset:5888
	v_add_u32_e32 v252, v208, v167
	ds_read_b128 v[248:251], v252 offset:8192
	v_exp_f32_e32 v80, v80
	v_exp_f32_e32 v81, v81
	v_add_f32_e32 v138, v78, v138
	v_add_f32_e32 v138, v79, v138
	v_cvt_pk_bf16_f32 v121, v72, v73
	v_add_f32_e32 v138, v80, v138
	v_add_f32_e32 v138, v81, v138
	v_cvt_pk_bf16_f32 v114, v74, v75
	v_cvt_pk_bf16_f32 v115, v76, v77
	v_cvt_pk_bf16_f32 v116, v78, v79
	v_cvt_pk_bf16_f32 v117, v80, v81
	s_nop 0
	v_cmp_ge_f32_e32 vcc, s70, v138
	s_cmp_eq_u64 vcc, exec
	s_cbranch_scc0 .Lfa0_slow
	v_add_f32_e32 v163, v163, v138
.Lfa0_slow_done:
	s_add_u32 s48, s48, 0x4000
	s_addc_u32 s49, s49, 0
	s_add_i32 s96, s96, 64
	s_mov_b32 s6, s95
	s_mov_b32 s95, s89
	s_mov_b32 s89, s33
	s_add_i32 s10, s97, s96
	s_abs_i32 s11, s10
	s_cmpk_lt_i32 s11, 0xda
	s_cbranch_scc1 .Lfa0_exit
	s_add_i32 s11, s96, 64
	s_cmpk_eq_i32 s11, 0x3f40
	s_cbranch_scc0 .Lfa0_loop
.Lfa0_exit:
	s_waitcnt lgkmcnt(0)
	s_barrier
	s_branch .LBB0_570
.Lfa0_shift:
	s_nop 7
	s_nop 7
	v_sub_f32_e32 v82, v82, v162
	v_sub_f32_e32 v83, v83, v162
	v_sub_f32_e32 v84, v84, v162
	v_sub_f32_e32 v85, v85, v162
	v_sub_f32_e32 v86, v86, v162
	v_sub_f32_e32 v87, v87, v162
	v_sub_f32_e32 v88, v88, v162
	v_sub_f32_e32 v89, v89, v162
	v_sub_f32_e32 v90, v90, v162
	v_sub_f32_e32 v91, v91, v162
	v_sub_f32_e32 v92, v92, v162
	v_sub_f32_e32 v93, v93, v162
	v_sub_f32_e32 v94, v94, v162
	v_sub_f32_e32 v95, v95, v162
	v_sub_f32_e32 v96, v96, v162
	v_sub_f32_e32 v97, v97, v162
	v_sub_f32_e32 v66, v66, v162
	v_sub_f32_e32 v67, v67, v162
	v_sub_f32_e32 v68, v68, v162
	v_sub_f32_e32 v69, v69, v162
	v_sub_f32_e32 v70, v70, v162
	v_sub_f32_e32 v71, v71, v162
	v_sub_f32_e32 v72, v72, v162
	v_sub_f32_e32 v73, v73, v162
	v_sub_f32_e32 v74, v74, v162
	v_sub_f32_e32 v75, v75, v162
	v_sub_f32_e32 v76, v76, v162
	v_sub_f32_e32 v77, v77, v162
	v_sub_f32_e32 v78, v78, v162
	v_sub_f32_e32 v79, v79, v162
	v_sub_f32_e32 v80, v80, v162
	v_sub_f32_e32 v81, v81, v162
	s_branch .Lfa0_shift_done
.Lfa0_slow:
	v_max_f32_e32 v252, v82, v83
	v_max3_f32 v252, v252, v84, v85
	v_max3_f32 v252, v252, v86, v87
	v_max3_f32 v252, v252, v88, v89
	v_max3_f32 v252, v252, v90, v91
	v_max3_f32 v252, v252, v92, v93
	v_max3_f32 v252, v252, v94, v95
	v_max3_f32 v252, v252, v96, v97
	v_max3_f32 v252, v252, v66, v67
	v_max3_f32 v252, v252, v68, v69
	v_max3_f32 v252, v252, v70, v71
	v_max3_f32 v252, v252, v72, v73
	v_max3_f32 v252, v252, v74, v75
	v_max3_f32 v252, v252, v76, v77
	v_max3_f32 v252, v252, v78, v79
	v_max3_f32 v252, v252, v80, v81
	v_mov_b32_e32 v253, v252
	s_nop 1
	v_permlane32_swap_b32_e32 v252, v253
	v_max_f32_e32 v252, v252, v253
	v_log_f32_e32 v253, v252
	v_cmp_lt_f32_e64 s[6:7], s70, v252
	s_mov_b64 s[46:47], -1
	s_nop 0
	v_cndmask_b32_e64 v253, 0, v253, s[6:7]
	v_exp_f32_e64 v139, -v253
	v_add_f32_e32 v162, v162, v253
	s_nop 0
	v_mul_f32_e32 v82, v82, v139
	v_mul_f32_e32 v83, v83, v139
	v_mul_f32_e32 v84, v84, v139
	v_mul_f32_e32 v85, v85, v139
	v_mul_f32_e32 v86, v86, v139
	v_mul_f32_e32 v87, v87, v139
	v_mul_f32_e32 v88, v88, v139
	v_mul_f32_e32 v89, v89, v139
	v_mul_f32_e32 v90, v90, v139
	v_mul_f32_e32 v91, v91, v139
	v_mul_f32_e32 v92, v92, v139
	v_mul_f32_e32 v93, v93, v139
	v_mul_f32_e32 v94, v94, v139
	v_mul_f32_e32 v95, v95, v139
	v_mul_f32_e32 v96, v96, v139
	v_mul_f32_e32 v97, v97, v139
	v_mul_f32_e32 v66, v66, v139
	v_mul_f32_e32 v67, v67, v139
	v_mul_f32_e32 v68, v68, v139
	v_mul_f32_e32 v69, v69, v139
	v_mul_f32_e32 v70, v70, v139
	v_mul_f32_e32 v71, v71, v139
	v_mul_f32_e32 v72, v72, v139
	v_mul_f32_e32 v73, v73, v139
	v_mul_f32_e32 v74, v74, v139
	v_mul_f32_e32 v75, v75, v139
	v_mul_f32_e32 v76, v76, v139
	v_mul_f32_e32 v77, v77, v139
	v_mul_f32_e32 v78, v78, v139
	v_mul_f32_e32 v79, v79, v139
	v_mul_f32_e32 v80, v80, v139
	v_mul_f32_e32 v81, v81, v139
	v_mul_f32_e32 v138, v138, v139
	v_cvt_pk_bf16_f32 v126, v82, v83
	v_cvt_pk_bf16_f32 v127, v84, v85
	v_cvt_pk_bf16_f32 v128, v86, v87
	v_cvt_pk_bf16_f32 v129, v88, v89
	v_cvt_pk_bf16_f32 v122, v90, v91
	v_cvt_pk_bf16_f32 v123, v92, v93
	v_cvt_pk_bf16_f32 v124, v94, v95
	v_cvt_pk_bf16_f32 v125, v96, v97
	v_cvt_pk_bf16_f32 v118, v66, v67
	v_cvt_pk_bf16_f32 v119, v68, v69
	v_cvt_pk_bf16_f32 v120, v70, v71
	v_cvt_pk_bf16_f32 v121, v72, v73
	v_cvt_pk_bf16_f32 v114, v74, v75
	v_cvt_pk_bf16_f32 v115, v76, v77
	v_cvt_pk_bf16_f32 v116, v78, v79
	v_cvt_pk_bf16_f32 v117, v80, v81
	v_fmac_f32_e32 v138, v163, v139
	v_mov_b32_e32 v163, v138
	s_and_saveexec_b64 s[6:7], s[4:5]
	ds_write_b32 v160, v139 offset:128
	s_or_b64 exec, exec, s[6:7]
	s_waitcnt lgkmcnt(0)
	v_add_u32_e32 v252, s75, v130
	ds_read_b128 v[82:85], v252 offset:224
	ds_read_b128 v[86:89], v252 offset:192
	ds_read_b128 v[90:93], v252 offset:160
	ds_read_b128 v[94:97], v252 offset:128
	s_waitcnt lgkmcnt(0)
	v_mul_f32_e32 v30, v30, v82
	v_mul_f32_e32 v31, v31, v83
	v_mul_f32_e32 v32, v32, v84
	v_mul_f32_e32 v33, v33, v85
	v_mul_f32_e32 v26, v26, v86
	v_mul_f32_e32 v27, v27, v87
	v_mul_f32_e32 v28, v28, v88
	v_mul_f32_e32 v29, v29, v89
	v_mul_f32_e32 v22, v22, v90
	v_mul_f32_e32 v23, v23, v91
	v_mul_f32_e32 v24, v24, v92
	v_mul_f32_e32 v25, v25, v93
	v_mul_f32_e32 v18, v18, v94
	v_mul_f32_e32 v19, v19, v95
	v_mul_f32_e32 v20, v20, v96
	v_mul_f32_e32 v21, v21, v97
	v_mul_f32_e32 v62, v62, v82
	v_mul_f32_e32 v63, v63, v83
	v_mul_f32_e32 v64, v64, v84
	v_mul_f32_e32 v65, v65, v85
	v_mul_f32_e32 v58, v58, v86
	v_mul_f32_e32 v59, v59, v87
	v_mul_f32_e32 v60, v60, v88
	v_mul_f32_e32 v61, v61, v89
	v_mul_f32_e32 v54, v54, v90
	v_mul_f32_e32 v55, v55, v91
	v_mul_f32_e32 v56, v56, v92
	v_mul_f32_e32 v57, v57, v93
	v_mul_f32_e32 v50, v50, v94
	v_mul_f32_e32 v51, v51, v95
	v_mul_f32_e32 v52, v52, v96
	v_mul_f32_e32 v53, v53, v97
	v_mul_f32_e32 v46, v46, v82
	v_mul_f32_e32 v47, v47, v83
	v_mul_f32_e32 v48, v48, v84
	v_mul_f32_e32 v49, v49, v85
	v_mul_f32_e32 v42, v42, v86
	v_mul_f32_e32 v43, v43, v87
	v_mul_f32_e32 v44, v44, v88
	v_mul_f32_e32 v45, v45, v89
	v_mul_f32_e32 v38, v38, v90
	v_mul_f32_e32 v39, v39, v91
	v_mul_f32_e32 v40, v40, v92
	v_mul_f32_e32 v41, v41, v93
	v_mul_f32_e32 v34, v34, v94
	v_mul_f32_e32 v35, v35, v95
	v_mul_f32_e32 v36, v36, v96
	v_mul_f32_e32 v37, v37, v97
	v_mul_f32_e32 v14, v14, v82
	v_mul_f32_e32 v15, v15, v83
	v_mul_f32_e32 v16, v16, v84
	v_mul_f32_e32 v17, v17, v85
	v_mul_f32_e32 v10, v10, v86
	v_mul_f32_e32 v11, v11, v87
	v_mul_f32_e32 v12, v12, v88
	v_mul_f32_e32 v13, v13, v89
	v_mul_f32_e32 v6, v6, v90
	v_mul_f32_e32 v7, v7, v91
	v_mul_f32_e32 v8, v8, v92
	v_mul_f32_e32 v9, v9, v93
	v_mul_f32_e32 v2, v2, v94
	v_mul_f32_e32 v3, v3, v95
	v_mul_f32_e32 v4, v4, v96
	v_mul_f32_e32 v5, v5, v97
	s_branch .Lfa0_slow_done
